# compress split-K GEMM moved to otherwise idle workgroups 192-255; SEL loop 2-deep K/V prefetch; SEL block mask folded into row max
# speedup vs baseline: 1.0207x; 1.0207x over previous
; #define lds fresh_lds(lds0)
;     DI bool next(int i, Unit& u) const {
;         const long L = (long)i * G + c; if (L >= nwg) return false;
; __global__ void __launch_bounds__(512) mega_fwd(Params P) {
;     ...
;             PHASE_PTRS; pg8::Gemm g{FLAT + ks * 512, Wc1 + ks * 512, 4096, 256, 512, 2048, 2048}; pg8::StaticOrder S; S.init(4096, 256, G, (bid + G - 128 - 16 * ks) % G);
;             pg8::EpiF32 E{WSP(float, WS_PART) + (size_t)ks * 4096 * 256, 256}; pg8::gemm_phase(lds, g, S, E, wv0); } }
.LBB0_851:
	s_mov_b32 s0, s81
	s_add_i32 s0, s0, 0x20040
	v_mov_b32_e32 v0, s0
	ds_read_b32 v2, v0 offset:200
	ds_read_b32 v0, v0 offset:204
	s_mov_b32 s0, 0
	s_add_i32 s0, s0, 0x20040
	s_waitcnt lgkmcnt(0)
	v_readfirstlane_b32 s4, v2
	v_readfirstlane_b32 s5, v0
	v_mov_b32_e32 v0, s0
	ds_read_b32 v2, v0 offset:192
	ds_read_b32 v0, v0 offset:196
	s_mov_b32 s27, s82
	s_mov_b32 s0, s75
	s_waitcnt lgkmcnt(0)
	v_mov_b32_e32 v0, v1
	s_mov_b32 s1, 0
	s_mov_b32 s1, 0
	s_lshl_b32 s1, s26, 4
	s_sub_i32 s1, s27, s1
	s_add_i32 s0, s1, s0
	s_add_i32 s1, s0, 0xffffff40
	s_sub_i32 s0, 0xc0, s0
	s_ashr_i32 s2, s1, 31
	s_max_i32 s0, s1, s0
	s_abs_i32 s1, s27
	v_cvt_f32_u32_e32 v0, s1
	s_sub_i32 s3, 0, s1
	s_mov_b32 s10, 0
	v_rcp_iflag_f32_e32 v0, v0
	s_nop 0
	v_mul_f32_e32 v0, 0x4f7ffffe, v0
	v_cvt_u32_f32_e32 v0, v0
	s_nop 0
	v_readfirstlane_b32 s6, v0
	s_mul_i32 s3, s3, s6
	s_mul_hi_u32 s3, s6, s3
	s_add_i32 s6, s6, s3
	s_mul_hi_u32 s3, s0, s6
	s_mul_i32 s3, s3, s1
	s_sub_i32 s0, s0, s3
	s_sub_i32 s3, s0, s1
	s_cmp_ge_u32 s0, s1
	s_cselect_b32 s0, s3, s0
	s_sub_i32 s3, s0, s1
	v_mov_b32_e32 v0, v1
	s_cmp_ge_u32 s0, s1
	s_cselect_b32 s0, s3, s0
	v_mbcnt_lo_u32_b32 v0, -1, v0
	s_xor_b32 s0, s0, s2
	v_mbcnt_hi_u32_b32 v15, -1, v0
	s_sub_i32 s28, s0, s2
	v_or_b32_e32 v0, s79, v15
	s_cmp_gt_i32 s28, 15
	v_readfirstlane_b32 s8, v0
	s_cbranch_scc1 .LBB0_850
	s_ashr_i32 s29, s28, 31
	s_lshr_b32 s0, s29, 29
	s_add_i32 s3, s28, s0
	s_and_b32 s0, s3, -8
	s_sub_i32 s6, s28, s0
	s_cmp_gt_i32 s6, -1
	s_mov_b64 s[0:1], -1
	s_cbranch_scc0 .LBB0_854
	s_lshl_b32 s2, s6, 1
	s_mov_b64 s[0:1], 0

; template <int DQK, int MODE> ...
;     ...
;     const int tid = fresh_tid2(wv0), lane = tid & 63, wid = wv0, r32 = lane & 31, hi = lane >> 5;
;     const int qpos = q0 + 32 * wid + r32, qmin = q0 + 32 * wid, qmax = qmin + 31;
;     bf16x8 qf[NKS];
; #pragma unroll
;     for (int ks = 0; ks < NKS; ++ks) qf[ks] = *(const bf16x8*)(Qp + (size_t)(32 * wid + r32) * qpitch + 16 * ks + 8 * hi);
;     if (DQK == 96) {
; #pragma unroll
;         for (int ks = 4; ks < NKS; ++ks) {
;             const int p0 = 8 * (ks - 4) + 4 * hi;
; __global__ void __launch_bounds__(512) mega_fwd(Params P) {
;     ...
;                 const int qb = 31 - it / 24, r24 = it % 24, bh = r24 % 12, b = bh / 6, h = bh % 6, g = h / 3, q0 = qb * 256;
;                 const size_t rb = (size_t)b * SEQ; const size_t qrow = rb + q0 + 32 * wid + r32;
;                 if (r24 < 12) {
;                     f32x16 tot[2]; tot[0] = (f32x16){}; tot[1] = (f32x16){};
;                     flash_unit<96, MODE_CAUSAL>(lds, wv0, QMLA + (rb + q0) * 576 + h * 96, 576, KVB + rb * 768 + h * 64, 768, PROJ + rb * NPROJ + PC_KR, NPROJ,
;                                                 KVB + rb * 768 + 384 + h * 64, 768, q0, 0, (q0 + 256) / 64, 0.10206207261596577f * LOG2E, (u32x4){}, 1.f, tot, nullptr, WSP(float, WS_ROPE));
;                     store_o(tot, HN + qrow * DM + h * 64, hi);
;                 } else {
;                     const float g1 = GATES[qrow * 32 + h * 3 + 1], g2 = GATES[qrow * 32 + h * 3 + 2];
;                     const u32x4 mw = *(const u32x4*)(MASKS + ((size_t)(b * 2 + g) * SEQ + q0 + 32 * wid + r32) * 4);
;                     f32x16 tot[2];
;                     { const bf16_t* oc = OCMP + qrow * 384 + h * 64;
; #pragma unroll
;                       for (int d0 = 0; d0 < 2; ++d0)
; #pragma unroll
;                           for (int j = 0; j < 4; ++j) { const u32x2 w = *(const u32x2*)(oc + 32 * d0 + 8 * j + 4 * hi); tot[d0][4 * j] = bflo(w.x); tot[d0][4 * j + 1] = bfhi(w.x); tot[d0][4 * j + 2] = bflo(w.y); tot[d0][4 * j + 3] = bfhi(w.y); } }
;                     const bf16_t* Qp = PROJ + (rb + q0) * NPROJ + PC_NQ + 64 * h;
;                     flash_unit<64, MODE_SEL>(lds, wv0, Qp, NPROJ, PROJ + rb * NPROJ + PC_KS + 64 * g, NPROJ, nullptr, 0, PROJ + rb * NPROJ + PC_VS + 64 * g, NPROJ,
;                                              q0, 0, (q0 + 256) / 64, 0.125f * LOG2E, mw, g1, tot, nullptr);
.LBB0_1306:
	s_or_b64 exec, exec, s[0:1]
	v_mov_b32_e32 v0, s38
	s_waitcnt lgkmcnt(0)
	s_barrier
	ds_read_b32 v0, v0
	s_movk_i32 s0, 0x3ff
	s_waitcnt lgkmcnt(0)
	v_cmp_lt_i32_e32 vcc, s0, v0
	v_readfirstlane_b32 s34, v0
	s_mov_b64 s[0:1], -1
	s_cbranch_vccnz .LBB0_1303
	s_cmpk_lt_i32 s34, 0x300
	s_cbranch_scc0 .LBB0_1372
	s_mul_hi_i32 s0, s34, 0xd5555555
	s_lshr_b32 s1, s0, 31
	s_lshr_b32 s0, s0, 2
	s_add_i32 s4, s0, s1
	s_mul_hi_i32 s0, s34, 0x2aaaaaab
	s_lshr_b32 s1, s0, 31
	s_lshr_b32 s0, s0, 2
	s_add_i32 s0, s0, s1
	s_mul_i32 s0, s0, 24
	s_sub_i32 s6, s34, s0
	s_mul_i32 s0, s6, 43
	s_sext_i32_i16 s1, s0
	s_lshr_b32 s1, s1, 9
	s_bfe_u32 s0, s0, 0x1000f
	s_add_i32 s0, s1, s0
	s_mul_i32 s0, s0, 12
	s_sub_i32 s1, s6, s0
	s_bfe_i32 s0, s1, 0x80000
	s_mul_i32 s0, s0, 43
	s_bfe_u32 s5, s0, 0x1000f
	s_bfe_u32 s0, s0, 0x80008
	s_add_i32 s0, s0, s5
	s_mul_i32 s5, s0, 6
	s_sub_i32 s1, s1, s5
	s_lshl_b32 s35, s4, 8
	s_bfe_i64 s[8:9], s[0:1], 0x80000
	s_add_i32 s36, s35, 0x1f00
	s_lshl_b64 s[4:5], s[8:9], 13
	s_add_u32 s26, s4, s36
	s_addc_u32 s27, s5, 0
	s_sext_i32_i8 s37, s1
	v_lshl_add_u64 v[180:181], s[26:27], 0, v[174:175]
	s_mov_b64 s[4:5], -1
	s_cmp_gt_i32 s6, 11
	s_mul_hi_i32 s45, s8, 0x2800000
	s_mul_i32 s46, s8, 0x2800000
	s_cbranch_scc0 .LBB0_1346
	s_bfe_i32 s1, s1, 0x80000
	s_mulk_i32 s1, 0x56
	s_bfe_u32 s4, s1, 0x1000f
	s_bfe_u32 s1, s1, 0x80008
	s_add_i32 s1, s1, s4
	s_sext_i32_i8 s6, s1
	s_sext_i32_i8 s0, s0
	s_lshl_b32 s0, s0, 14
	s_lshl_b32 s1, s6, 13
	s_add_i32 s1, s1, s0
	s_add_u32 s0, s1, s36
	s_addc_u32 s1, 0, 0
	v_mov_b64_e32 v[6:7], s[18:19]
	v_lshl_add_u64 v[4:5], s[0:1], 0, v[174:175]
	v_mad_u64_u32 v[6:7], s[0:1], v180, s72, v[6:7]
	v_mov_b32_e32 v0, v7
	v_lshlrev_b64 v[2:3], 7, v[180:181]
	v_mad_u64_u32 v[8:9], s[0:1], v181, s72, v[0:1]
	s_mul_i32 s80, s37, 3
	v_lshl_add_u64 v[2:3], s[14:15], 0, v[2:3]
	s_mul_i32 s0, s27, 0x1400
	s_mul_hi_u32 s1, s26, 0x1400
	v_lshl_add_u64 v[2:3], s[80:81], 2, v[2:3]
	s_lshl_b32 s9, s37, 6
	s_lshl_b32 s80, s37, 7
	s_add_i32 s1, s1, s0
	s_mul_i32 s0, s26, 0x1400
	s_add_u32 s0, s39, s0
	v_mov_b32_e32 v7, v8
	s_addc_u32 s1, s40, s1
	v_lshl_add_u64 v[6:7], v[6:7], 0, s[80:81]
	v_mov_b32_e32 v179, v1
	s_add_u32 s30, s0, s80
	v_lshl_add_u64 v[4:5], v[4:5], 4, s[16:17]
	v_lshl_add_u64 v[6:7], v[6:7], 0, v[178:179]
	s_addc_u32 s31, s1, 0
	s_mov_b32 s1, s81
	v_mov_b32_e32 v0, v1
	flat_load_dwordx2 v[182:183], v[2:3] offset:4
	s_nop 0
	flat_load_dwordx4 v[2:5], v[4:5]
	s_nop 0
	flat_load_dwordx2 v[198:199], v[6:7]
	flat_load_dwordx2 v[196:197], v[6:7] offset:16
	flat_load_dwordx2 v[194:195], v[6:7] offset:32
	flat_load_dwordx2 v[192:193], v[6:7] offset:48
	flat_load_dwordx2 v[190:191], v[6:7] offset:64
	flat_load_dwordx2 v[188:189], v[6:7] offset:80
	flat_load_dwordx2 v[186:187], v[6:7] offset:96
	flat_load_dwordx2 v[184:185], v[6:7] offset:112
	v_readlane_b32 s7, v254, 6
	v_mbcnt_lo_u32_b32 v0, -1, v0
	v_mbcnt_hi_u32_b32 v26, -1, v0
	v_and_b32_e32 v27, 31, v26
	v_bfe_u32 v28, v26, 5, 1
	v_or_b32_e32 v0, s7, v27
	v_mov_b64_e32 v[6:7], s[30:31]
	v_mad_i64_i32 v[6:7], s[4:5], v0, s69, v[6:7]
	v_lshlrev_b32_e32 v0, 4, v28
	v_lshl_add_u64 v[6:7], v[6:7], 0, v[0:1]
	s_waitcnt vmcnt(0)
	flat_load_dwordx4 v[84:87], v[6:7] offset:832
	flat_load_dwordx4 v[80:83], v[6:7] offset:864
	flat_load_dwordx4 v[10:13], v[6:7] offset:896
	s_nop 0
	flat_load_dwordx4 v[6:9], v[6:7] offset:928
	s_add_u32 s0, s39, s46
	v_or_b32_e32 v14, s79, v26
	s_addc_u32 s4, s40, s45
	s_lshl_b32 s5, s6, 7
	v_and_b32_e32 v15, 7, v26
	v_ashrrev_i32_e32 v24, 3, v14
	s_add_u32 s28, s0, s5
	v_lshlrev_b32_e32 v29, 4, v15
	v_mul_lo_u32 v14, v24, s69
	v_mov_b32_e32 v23, v1
	s_addc_u32 s29, s4, 0
	v_or_b32_e32 v22, v29, v14
	v_lshl_add_u64 v[18:19], s[28:29], 0, v[22:23]
	s_movk_i32 s4, 0x90
	v_mul_lo_u32 v23, v24, s4
	v_mov_b32_e32 v25, v1
	v_add3_u32 v129, s1, v23, v29
	v_add_u32_e32 v24, 0x50000, v22
	v_lshl_add_u64 v[24:25], s[28:29], 0, v[24:25]
	v_add_u32_e32 v226, 0xa0000, v22
	v_mov_b32_e32 v227, v1
	v_lshl_add_u64 v[226:227], s[28:29], 0, v[226:227]
	v_mad_u32_u24 v131, v27, s4, v0
	v_lshlrev_b32_e32 v128, 2, v28
	v_lshrrev_b32_e32 v0, 2, v26
	s_add_i32 s0, s35, 0x2000
	s_add_i32 s48, s36, s7
	v_and_or_b32 v0, v0, 3, v128
	v_mov_b32_e32 v30, v1
	v_mov_b32_e32 v31, v1
	s_lshr_b32 s47, s0, 6
	v_mov_b32_e32 v23, v1
	v_mov_b32_e32 v28, v1
	v_mov_b32_e32 v29, v1
	s_mov_b32 s53, s81
	s_mov_b32 s50, 0
	s_or_b32 s49, s48, 31
	s_add_i32 s0, s47, -1
	v_mov_b32_e32 v179, 0
	s_mov_b32 s51, 63
	s_waitcnt vmcnt(0) lgkmcnt(0)
	global_load_dwordx4 v[14:17], v[18:19], off offset:2112
	s_nop 0
	global_load_dwordx4 v[18:21], v[18:19], off offset:2368
	global_load_dwordx4 v[88:91], v[24:25], off offset:2368
	global_load_dwordx4 v[92:95], v[24:25], off offset:2112
	global_load_dwordx4 v[222:225], v[226:227], off offset:2368
	global_load_dwordx4 v[218:221], v[226:227], off offset:2112
	s_waitcnt lgkmcnt(0)
	s_barrier
	s_waitcnt vmcnt(4)
	ds_write_b128 v129, v[14:17]
	ds_write_b128 v129, v[18:21] offset:28672
	v_lshlrev_b32_e32 v14, 1, v26
	v_and_b32_e32 v14, 32, v14
	v_lshlrev_b32_e32 v16, 3, v26
	v_and_or_b32 v14, v16, 24, v14
	v_or_b32_e32 v15, s48, v27
	v_mad_u32_u24 v130, v0, s4, v14
	v_add_u32_e32 v0, 0xf0000, v22
	v_mov_b32_e32 v16, v1
	v_mov_b32_e32 v17, v1
	v_mov_b32_e32 v18, v1
	v_mov_b32_e32 v19, v1
	v_mov_b32_e32 v20, v1
	v_mov_b32_e32 v21, v1
	v_mov_b32_e32 v22, v1
	v_mov_b32_e32 v24, v1
	v_mov_b32_e32 v25, v1
	v_mov_b32_e32 v26, v1
	v_mov_b32_e32 v27, v1
	v_mov_b64_e32 v[46:47], v[30:31]
	v_mov_b32_e32 v14, 0xf149f2ca
	v_mov_b64_e32 v[44:45], v[28:29]
	v_mov_b64_e32 v[42:43], v[26:27]
	v_mov_b64_e32 v[40:41], v[24:25]
	v_mov_b64_e32 v[38:39], v[22:23]
	v_mov_b64_e32 v[36:37], v[20:21]
	v_mov_b64_e32 v[34:35], v[18:19]
	v_mov_b64_e32 v[32:33], v[16:17]
	s_waitcnt lgkmcnt(0)
	s_barrier
	s_branch .LBB0_1311

; template <int DQK, int MODE> ...
;     ...
;             if (MODE == MODE_SEL) {
;                 const unsigned w = (t < 32) ? mw.x : (t < 64) ? mw.y : (t < 96) ? mw.z : mw.w; const bool selw = ((w >> (t & 31)) & 1u) != 0;
;                 if (!__all(selw)) {
; #pragma unroll
;                     for (int kb = 0; kb < 2; ++kb)
; #pragma unroll
;                         for (int i = 0; i < 16; ++i) s[kb][i] = selw ? s[kb][i] : -INFINITY;
;                 }
;             }
;             float mx = fmaxf(s[0][0], s[1][0]);
; #pragma unroll
;             for (int i = 1; i < 16; ++i) mx = fmaxf(fmaxf(mx, s[0][i]), s[1][i]);
;             mx = half_max(mx);
;             const float msc = mx * sc;
;             if (__any(msc > mref + 8.f)) {
;                 const float mnew = fmaxf(mref, msc), alpha = __builtin_amdgcn_exp2f(mref - mnew);
;                 mref = mnew; l *= alpha;
; #pragma unroll
;                 for (int i = 0; i < 16; ++i) { o[0][i] *= alpha; o[1][i] *= alpha; }
;             }
;             float ls = 0.f;
; #pragma unroll
;             for (int kb = 0; kb < 2; ++kb)
; #pragma unroll
;                 for (int i = 0; i < 16; ++i) { const float p = __builtin_amdgcn_exp2f(__builtin_fmaf(s[kb][i], sc, -mref)); s[kb][i] = p; ls += p; }
;             l += ls;
;             {
;                 asm volatile("s_waitcnt lgkmcnt(0)" ::: "memory");
; #pragma unroll
;                 for (int kb = 0; kb < 2; ++kb)
; #pragma unroll
;                     for (int s2 = 0; s2 < 2; ++s2)
; #pragma unroll
;                         for (int d0 = 0; d0 < 2; ++d0) { asm volatile("" : "+v"(vlo[kb][s2][d0]), "+v"(vhi[kb][s2][d0])); }
;                 __builtin_amdgcn_s_setprio(1);
; #pragma unroll
;                 for (int kb = 0; kb < 2; ++kb)
; #pragma unroll
;                     for (int s2 = 0; s2 < 2; ++s2) {
;                         const bf16x8 pf = pack8(s[kb], s2);
; #pragma unroll
;                         for (int d0 = 0; d0 < 2; ++d0) {
;                             const s16x4 lo = vlo[kb][s2][d0], hh = vhi[kb][s2][d0];
;                             const bf16x8 vfr = (bf16x8){lo[0], lo[1], lo[2], lo[3], hh[0], hh[1], hh[2], hh[3]};
;                             o[d0] = MFMA32(vfr, pf, o[d0]);
;                         }
;                     }
;                 __builtin_amdgcn_s_setprio(0);
;             }
;         }
.LBB0_1314:
	s_cmp_lt_u32 s50, 32
	s_cselect_b64 vcc, -1, 0
	s_cmp_lt_u32 s50, 64
	s_cselect_b64 s[4:5], -1, 0
	s_cmpk_lt_u32 s50, 0x60
	s_cselect_b64 s[6:7], -1, 0
	v_cndmask_b32_e64 v132, v5, v4, s[6:7]
	v_cndmask_b32_e64 v132, v132, v3, s[4:5]
	v_cndmask_b32_e32 v132, v132, v2, vcc
	s_and_b32 s4, s50, 31
	v_bfe_u32 v132, v132, s4, 1
	v_cmp_ne_u32_e64 s[6:7], 0, v132
.LBB0_1316:
	v_max_f32_e32 v132, v48, v48
	v_max_f32_e32 v133, v64, v64
	v_max_f32_e32 v132, v133, v132
	v_max3_f32 v132, v132, v65, v49
	v_max3_f32 v132, v132, v66, v50
	v_max3_f32 v132, v132, v67, v51
	v_max3_f32 v132, v132, v68, v52
	v_max3_f32 v132, v132, v69, v53
	v_max3_f32 v132, v132, v70, v54
	v_max3_f32 v132, v132, v71, v55
	v_max3_f32 v132, v132, v72, v56
	v_max3_f32 v132, v132, v73, v57
	v_max3_f32 v132, v132, v74, v58
	v_max3_f32 v132, v132, v75, v59
	v_max3_f32 v132, v132, v76, v60
	v_max3_f32 v132, v132, v77, v61
	v_max3_f32 v132, v132, v78, v62
	v_max3_f32 v132, v132, v79, v63
	v_mov_b32_e32 v133, v132
	s_nop 1
	v_permlane32_swap_b32_e32 v132, v133
	v_max_f32_e32 v133, v133, v133
	v_max_f32_e32 v132, v132, v132
	v_max_f32_e32 v132, v132, v133
	v_cndmask_b32_e64 v132, v204, v132, s[6:7]
	v_mul_f32_e32 v132, 0x3e38aa3b, v132
	v_add_f32_e32 v133, 0x41000000, v14
	v_cmp_gt_f32_e32 vcc, v132, v133
	s_cbranch_vccz .LBB0_1318
	v_max_f32_e32 v132, v132, v132
	v_max_f32_e32 v133, v14, v14
	v_max_f32_e32 v132, v133, v132
	v_sub_f32_e32 v14, v14, v132
	v_exp_f32_e32 v14, v14
	s_nop 0
	v_pk_mul_f32 v[46:47], v[46:47], v[14:15] op_sel_hi:[1,0]
	v_pk_mul_f32 v[44:45], v[44:45], v[14:15] op_sel_hi:[1,0]
	v_pk_mul_f32 v[42:43], v[42:43], v[14:15] op_sel_hi:[1,0]
	v_pk_mul_f32 v[40:41], v[40:41], v[14:15] op_sel_hi:[1,0]
	v_pk_mul_f32 v[38:39], v[38:39], v[14:15] op_sel_hi:[1,0]
	v_pk_mul_f32 v[36:37], v[36:37], v[14:15] op_sel_hi:[1,0]
	v_pk_mul_f32 v[34:35], v[34:35], v[14:15] op_sel_hi:[1,0]
	v_pk_mul_f32 v[32:33], v[32:33], v[14:15] op_sel_hi:[1,0]
	v_pk_mul_f32 v[30:31], v[30:31], v[14:15] op_sel_hi:[1,0]
	v_pk_mul_f32 v[28:29], v[28:29], v[14:15] op_sel_hi:[1,0]
	v_pk_mul_f32 v[26:27], v[26:27], v[14:15] op_sel_hi:[1,0]
	v_pk_mul_f32 v[24:25], v[24:25], v[14:15] op_sel_hi:[1,0]
	v_pk_mul_f32 v[22:23], v[22:23], v[14:15] op_sel_hi:[1,0]
	v_pk_mul_f32 v[20:21], v[20:21], v[14:15] op_sel_hi:[1,0]
	v_pk_mul_f32 v[18:19], v[18:19], v[14:15] op_sel_hi:[1,0]
	v_pk_mul_f32 v[16:17], v[16:17], v[14:15] op_sel_hi:[1,0]
	v_mul_f32_e32 v179, v179, v14
	v_mov_b32_e32 v14, v132
.LBB0_1318:
	v_xor_b32_e32 v217, 0x80000000, v14
	v_cndmask_b32_e64 v217, v204, v217, s[6:7]
	v_fma_f32 v64, v64, s78, v217
	v_exp_f32_e32 v64, v64
	v_fma_f32 v65, v65, s78, v217
	v_exp_f32_e32 v65, v65
	v_fma_f32 v66, v66, s78, v217
	v_exp_f32_e32 v66, v66
	v_fma_f32 v67, v67, s78, v217
	v_exp_f32_e32 v67, v67
	v_fma_f32 v68, v68, s78, v217
	v_add_f32_e32 v132, 0, v64
	v_exp_f32_e32 v68, v68
	v_fma_f32 v69, v69, s78, v217
	v_add_f32_e32 v132, v65, v132
	v_exp_f32_e32 v69, v69
	v_fma_f32 v70, v70, s78, v217
	v_add_f32_e32 v132, v66, v132
	v_exp_f32_e32 v70, v70
	v_fma_f32 v71, v71, s78, v217
	v_add_f32_e32 v132, v67, v132
	v_exp_f32_e32 v71, v71
	v_fma_f32 v72, v72, s78, v217
	v_add_f32_e32 v132, v68, v132
	v_exp_f32_e32 v72, v72
	v_fma_f32 v73, v73, s78, v217
	v_add_f32_e32 v132, v69, v132
	v_exp_f32_e32 v73, v73
	v_fma_f32 v74, v74, s78, v217
	v_add_f32_e32 v132, v70, v132
	v_exp_f32_e32 v74, v74
	v_fma_f32 v75, v75, s78, v217
	v_add_f32_e32 v132, v71, v132
	v_exp_f32_e32 v75, v75
	v_fma_f32 v76, v76, s78, v217
	v_add_f32_e32 v132, v72, v132
	v_exp_f32_e32 v76, v76
	v_fma_f32 v77, v77, s78, v217
	v_add_f32_e32 v132, v73, v132
	v_exp_f32_e32 v77, v77
	v_fma_f32 v78, v78, s78, v217
	v_add_f32_e32 v132, v74, v132
	v_exp_f32_e32 v78, v78
	v_fma_f32 v79, v79, s78, v217
	v_add_f32_e32 v132, v75, v132
	v_exp_f32_e32 v79, v79
	v_fma_f32 v48, v48, s78, v217
	v_add_f32_e32 v132, v76, v132
	v_exp_f32_e32 v133, v48
	v_fma_f32 v48, v49, s78, v217
	v_add_f32_e32 v132, v77, v132
	v_exp_f32_e32 v134, v48
	v_fma_f32 v48, v50, s78, v217
	v_add_f32_e32 v132, v78, v132
	v_exp_f32_e32 v135, v48
	v_fma_f32 v48, v51, s78, v217
	v_add_f32_e32 v132, v79, v132
	v_exp_f32_e32 v136, v48
	v_fma_f32 v49, v52, s78, v217
	v_add_f32_e32 v48, v133, v132
	v_exp_f32_e32 v52, v49
	v_fma_f32 v49, v53, s78, v217
	v_add_f32_e32 v48, v134, v48
	v_exp_f32_e32 v53, v49
	v_fma_f32 v49, v54, s78, v217
	v_add_f32_e32 v48, v135, v48
	v_exp_f32_e32 v54, v49
	v_fma_f32 v49, v55, s78, v217
	v_add_f32_e32 v48, v136, v48
	v_exp_f32_e32 v55, v49
	v_fma_f32 v49, v56, s78, v217
	v_add_f32_e32 v48, v52, v48
	v_exp_f32_e32 v56, v49
	v_fma_f32 v49, v57, s78, v217
	v_add_f32_e32 v48, v53, v48
	v_exp_f32_e32 v57, v49
	v_fma_f32 v49, v58, s78, v217
	v_add_f32_e32 v48, v54, v48
	v_exp_f32_e32 v58, v49
	v_fma_f32 v49, v59, s78, v217
	v_add_f32_e32 v48, v55, v48
	v_exp_f32_e32 v59, v49
	v_fma_f32 v49, v60, s78, v217
	v_add_f32_e32 v48, v56, v48
	v_exp_f32_e32 v60, v49
	v_fma_f32 v49, v61, s78, v217
	v_add_f32_e32 v48, v57, v48
	v_exp_f32_e32 v61, v49
	v_fma_f32 v49, v62, s78, v217
	v_add_f32_e32 v48, v58, v48
	v_exp_f32_e32 v62, v49
	v_fma_f32 v49, v63, s78, v217
	v_add_f32_e32 v48, v59, v48
	v_exp_f32_e32 v63, v49
	v_add_f32_e32 v48, v60, v48
	s_waitcnt lgkmcnt(0)
	v_add_f32_e32 v48, v61, v48
	v_add_f32_e32 v48, v62, v48
	v_add_f32_e32 v132, v63, v48
	s_setprio 1
	v_cvt_pk_bf16_f32 v48, v64, v65
	v_cvt_pk_bf16_f32 v49, v66, v67
	v_cvt_pk_bf16_f32 v50, v68, v69
	v_cvt_pk_bf16_f32 v51, v70, v71
	v_add_f32_e32 v179, v179, v132
	s_nop 0
	v_mfma_f32_32x32x16_bf16 v[32:47], v[116:119], v[48:51], v[32:47]
	v_mfma_f32_32x32x16_bf16 v[16:31], v[112:115], v[48:51], v[16:31]
	v_cvt_pk_bf16_f32 v48, v72, v73
	v_cvt_pk_bf16_f32 v49, v74, v75
	v_cvt_pk_bf16_f32 v50, v76, v77
	v_cvt_pk_bf16_f32 v51, v78, v79
	s_nop 1
	v_mfma_f32_32x32x16_bf16 v[32:47], v[100:103], v[48:51], v[32:47]
	v_mfma_f32_32x32x16_bf16 v[16:31], v[96:99], v[48:51], v[16:31]
	v_cvt_pk_bf16_f32 v48, v133, v134
	v_cvt_pk_bf16_f32 v49, v135, v136
	v_cvt_pk_bf16_f32 v50, v52, v53
	v_cvt_pk_bf16_f32 v51, v54, v55
	s_nop 1
	v_mfma_f32_32x32x16_bf16 v[32:47], v[124:127], v[48:51], v[32:47]
	v_mfma_f32_32x32x16_bf16 v[16:31], v[120:123], v[48:51], v[16:31]
	v_cvt_pk_bf16_f32 v48, v56, v57
	v_cvt_pk_bf16_f32 v49, v58, v59
	v_cvt_pk_bf16_f32 v50, v60, v61
	v_cvt_pk_bf16_f32 v51, v62, v63
	s_nop 1
	v_mfma_f32_32x32x16_bf16 v[32:47], v[108:111], v[48:51], v[32:47]
	v_mfma_f32_32x32x16_bf16 v[16:31], v[104:107], v[48:51], v[16:31]
	s_setprio 0
.LBB0_1319:
	s_xor_b32 s4, s52, 1
	s_mulk_i32 s4, 0x2400
	v_add_u32_e32 v48, s4, v129
	s_add_i32 s4, s50, 2
	s_cmp_ge_u32 s4, s47
	s_cbranch_scc1 .Lsel_w0
	s_waitcnt vmcnt(2)
	s_branch .Lsel_w1

; #define FL_LSTORE(buf) do { *(LAS u32x4*)(lds + AT_K + (buf) * KBUF + srow * KP2 + sch * 16) = rk1; \
;         if (DQK == 96 && tid < 256) *(LAS u32x4*)(lds + AT_K + (buf) * KBUF + srow2 * KP2 + 128 + sch2 * 16) = rk2; \
;         *(LAS u32x4*)(lds + AT_V + (buf) * VBUF + srow * VP2 + sch * 16) = rv; } while (0)
; template <int DQK, int MODE> ...
;     ...
;         if (t + 1 < t1) { FL_LSTORE(cur ^ 1); if (t + 2 < t1) FL_GLOAD(t + 2); }
;         __syncthreads();
.Lsel_w1:
	s_add_i32 s4, s50, 3
	s_cmp_lg_u32 s52, 0
	s_cbranch_scc1 .Lsel_odd
	ds_write_b128 v48, v[92:95]
	ds_write_b128 v48, v[88:91] offset:28672
	s_cmp_ge_u32 s4, s47
	s_cbranch_scc1 .LBB0_1310
	v_lshl_add_u64 v[48:49], s[28:29], 0, v[0:1]
	global_load_dwordx4 v[92:95], v[48:49], off offset:2112
	global_load_dwordx4 v[88:91], v[48:49], off offset:2368
	s_branch .LBB0_1310
.Lsel_odd:
	ds_write_b128 v48, v[218:221]
	ds_write_b128 v48, v[222:225] offset:28672
	s_cmp_ge_u32 s4, s47
	s_cbranch_scc1 .LBB0_1310
	v_lshl_add_u64 v[48:49], s[28:29], 0, v[0:1]
	global_load_dwordx4 v[218:221], v[48:49], off offset:2112
	global_load_dwordx4 v[222:225], v[48:49], off offset:2368
	s_branch .LBB0_1310
